# counted lgkmcnt waits extended to the layer-1 256x128 K-loops (w_out, mlp2)
# speedup vs baseline: 1.0014x; 1.0014x over previous
.LBB0_990:
	s_mul_i32 s10, s3, 0x6000
	s_add_i32 s10, s10, 0
	s_waitcnt vmcnt(6)
	v_add3_u32 v146, s10, v149, v150
	s_waitcnt lgkmcnt(0)
	s_barrier
	v_add3_u32 v248, s10, v148, v150
	ds_read_b128 v[184:187], v248 offset:16384
	ds_read_b128 v[188:191], v248 offset:17408
	ds_read_b128 v[192:195], v248 offset:18432
	ds_read_b128 v[196:199], v248 offset:19456
	ds_read_b128 v[142:145], v146
	ds_read_b128 v[156:159], v146 offset:1024
	ds_read_b128 v[160:163], v146 offset:2048
	ds_read_b128 v[164:167], v146 offset:3072
	ds_read_b128 v[168:171], v146 offset:4096
	ds_read_b128 v[172:175], v146 offset:5120
	ds_read_b128 v[176:179], v146 offset:6144
	ds_read_b128 v[180:183], v146 offset:7168
	s_cmp_gt_i32 s3, 0
	s_cselect_b32 s10, -1, 2
	s_add_i32 s10, s10, s3
	s_mul_i32 s12, s10, 0x6000
	v_lshl_add_u64 v[146:147], v[140:141], 0, s[6:7]
	s_mov_b64 s[10:11], 0x130e0080
	s_add_i32 s12, s2, s12
	v_lshl_add_u64 v[200:201], v[146:147], 0, s[10:11]
	s_mov_b32 m0, s12
	s_mov_b64 s[10:11], 0x13100080
	global_load_lds_dwordx4 v[200:201], off
	v_lshl_add_u64 v[200:201], v[146:147], 0, s[10:11]
	s_add_i32 m0, s12, 0x1000
	s_mov_b64 s[10:11], 0x13120080
	global_load_lds_dwordx4 v[200:201], off
	v_lshl_add_u64 v[200:201], v[146:147], 0, s[10:11]
	s_add_i32 m0, s12, 0x2000
	s_mov_b64 s[10:11], 0x13140080
	global_load_lds_dwordx4 v[200:201], off
	v_lshl_add_u64 v[146:147], v[146:147], 0, s[10:11]
	s_add_i32 m0, s12, 0x3000
	s_mov_b64 s[10:11], 0x1930080
	global_load_lds_dwordx4 v[146:147], off
	v_lshl_add_u64 v[146:147], v[138:139], 0, s[6:7]
	v_lshl_add_u64 v[200:201], v[146:147], 0, s[10:11]
	s_add_i32 m0, s12, 0x4000
	s_mov_b64 s[10:11], 0x1950080
	global_load_lds_dwordx4 v[200:201], off
	v_lshl_add_u64 v[146:147], v[146:147], 0, s[10:11]
	s_add_i32 m0, s12, 0x5000
	s_nop 0
	global_load_lds_dwordx4 v[146:147], off
	s_setprio 1
	s_waitcnt lgkmcnt(7)
	v_mfma_f32_16x16x32_bf16 v[126:129], v[184:187], v[142:145], v[126:129]
	v_mfma_f32_16x16x32_bf16 v[122:125], v[188:191], v[142:145], v[122:125]
	v_mfma_f32_16x16x32_bf16 v[118:121], v[192:195], v[142:145], v[118:121]
	v_mfma_f32_16x16x32_bf16 v[114:117], v[196:199], v[142:145], v[114:117]
	s_waitcnt lgkmcnt(6)
	v_mfma_f32_16x16x32_bf16 v[110:113], v[184:187], v[156:159], v[110:113]
	v_mfma_f32_16x16x32_bf16 v[106:109], v[188:191], v[156:159], v[106:109]
	v_mfma_f32_16x16x32_bf16 v[102:105], v[192:195], v[156:159], v[102:105]
	v_mfma_f32_16x16x32_bf16 v[98:101], v[196:199], v[156:159], v[98:101]
	s_waitcnt lgkmcnt(5)
	v_mfma_f32_16x16x32_bf16 v[94:97], v[184:187], v[160:163], v[94:97]
	v_mfma_f32_16x16x32_bf16 v[90:93], v[188:191], v[160:163], v[90:93]
	v_mfma_f32_16x16x32_bf16 v[86:89], v[192:195], v[160:163], v[86:89]
	v_mfma_f32_16x16x32_bf16 v[82:85], v[196:199], v[160:163], v[82:85]
	s_waitcnt lgkmcnt(4)
	v_mfma_f32_16x16x32_bf16 v[78:81], v[184:187], v[164:167], v[78:81]
	v_mfma_f32_16x16x32_bf16 v[74:77], v[188:191], v[164:167], v[74:77]
	v_mfma_f32_16x16x32_bf16 v[70:73], v[192:195], v[164:167], v[70:73]
	v_mfma_f32_16x16x32_bf16 v[66:69], v[196:199], v[164:167], v[66:69]
	s_waitcnt lgkmcnt(3)
	v_mfma_f32_16x16x32_bf16 v[62:65], v[184:187], v[168:171], v[62:65]
	v_mfma_f32_16x16x32_bf16 v[58:61], v[188:191], v[168:171], v[58:61]
	v_mfma_f32_16x16x32_bf16 v[54:57], v[192:195], v[168:171], v[54:57]
	v_mfma_f32_16x16x32_bf16 v[50:53], v[196:199], v[168:171], v[50:53]
	s_waitcnt lgkmcnt(2)
	v_mfma_f32_16x16x32_bf16 v[46:49], v[184:187], v[172:175], v[46:49]
	v_mfma_f32_16x16x32_bf16 v[42:45], v[188:191], v[172:175], v[42:45]
	v_mfma_f32_16x16x32_bf16 v[38:41], v[192:195], v[172:175], v[38:41]
	v_mfma_f32_16x16x32_bf16 v[34:37], v[196:199], v[172:175], v[34:37]
	s_waitcnt lgkmcnt(1)
	v_mfma_f32_16x16x32_bf16 v[30:33], v[184:187], v[176:179], v[30:33]
	v_mfma_f32_16x16x32_bf16 v[26:29], v[188:191], v[176:179], v[26:29]
	v_mfma_f32_16x16x32_bf16 v[22:25], v[192:195], v[176:179], v[22:25]
	v_mfma_f32_16x16x32_bf16 v[18:21], v[196:199], v[176:179], v[18:21]
	s_waitcnt lgkmcnt(0)
	v_mfma_f32_16x16x32_bf16 v[14:17], v[184:187], v[180:183], v[14:17]
	v_mfma_f32_16x16x32_bf16 v[10:13], v[188:191], v[180:183], v[10:13]
	v_mfma_f32_16x16x32_bf16 v[6:9], v[192:195], v[180:183], v[6:9]
	v_mfma_f32_16x16x32_bf16 v[2:5], v[196:199], v[180:183], v[2:5]
	s_setprio 0
	s_add_i32 s3, s3, 1
	s_cmp_lg_u32 s3, 3
	s_cselect_b32 s3, s3, 0
	s_add_u32 s6, s6, 64
	s_addc_u32 s7, s7, 0
	s_cmpk_eq_i32 s6, 0x780
	s_cbranch_scc0 .LBB0_990
	s_waitcnt vmcnt(6)
	s_waitcnt lgkmcnt(0)
	s_barrier
	ds_read_b128 v[138:141], v153
	ds_read_b128 v[142:145], v153 offset:1024
	ds_read_b128 v[156:159], v153 offset:2048
	ds_read_b128 v[160:163], v153 offset:3072
	ds_read_b128 v[164:167], v153 offset:4096
	ds_read_b128 v[168:171], v153 offset:5120
	ds_read_b128 v[172:175], v153 offset:6144
	ds_read_b128 v[176:179], v153 offset:7168
	ds_read_b128 v[180:183], v154 offset:16384
	ds_read_b128 v[184:187], v154 offset:17408
	ds_read_b128 v[188:191], v154 offset:18432
	ds_read_b128 v[192:195], v154 offset:19456
	s_setprio 1
	s_waitcnt lgkmcnt(0)
	v_mfma_f32_16x16x32_bf16 v[126:129], v[180:183], v[138:141], v[126:129]
	v_mfma_f32_16x16x32_bf16 v[122:125], v[184:187], v[138:141], v[122:125]
	v_mfma_f32_16x16x32_bf16 v[118:121], v[188:191], v[138:141], v[118:121]
	v_mfma_f32_16x16x32_bf16 v[114:117], v[192:195], v[138:141], v[114:117]
	v_mfma_f32_16x16x32_bf16 v[110:113], v[180:183], v[142:145], v[110:113]
	v_mfma_f32_16x16x32_bf16 v[106:109], v[184:187], v[142:145], v[106:109]
	v_mfma_f32_16x16x32_bf16 v[102:105], v[188:191], v[142:145], v[102:105]
	v_mfma_f32_16x16x32_bf16 v[98:101], v[192:195], v[142:145], v[98:101]
	v_mfma_f32_16x16x32_bf16 v[94:97], v[180:183], v[156:159], v[94:97]
	v_mfma_f32_16x16x32_bf16 v[90:93], v[184:187], v[156:159], v[90:93]
	v_mfma_f32_16x16x32_bf16 v[86:89], v[188:191], v[156:159], v[86:89]
	v_mfma_f32_16x16x32_bf16 v[82:85], v[192:195], v[156:159], v[82:85]
	v_mfma_f32_16x16x32_bf16 v[78:81], v[180:183], v[160:163], v[78:81]
	v_mfma_f32_16x16x32_bf16 v[74:77], v[184:187], v[160:163], v[74:77]
	v_mfma_f32_16x16x32_bf16 v[70:73], v[188:191], v[160:163], v[70:73]
	v_mfma_f32_16x16x32_bf16 v[66:69], v[192:195], v[160:163], v[66:69]
	v_mfma_f32_16x16x32_bf16 v[62:65], v[180:183], v[164:167], v[62:65]
	v_mfma_f32_16x16x32_bf16 v[58:61], v[184:187], v[164:167], v[58:61]
	v_mfma_f32_16x16x32_bf16 v[54:57], v[188:191], v[164:167], v[54:57]
	v_mfma_f32_16x16x32_bf16 v[50:53], v[192:195], v[164:167], v[50:53]
	v_mfma_f32_16x16x32_bf16 v[46:49], v[180:183], v[168:171], v[46:49]
	v_mfma_f32_16x16x32_bf16 v[42:45], v[184:187], v[168:171], v[42:45]
	v_mfma_f32_16x16x32_bf16 v[38:41], v[188:191], v[168:171], v[38:41]
	v_mfma_f32_16x16x32_bf16 v[34:37], v[192:195], v[168:171], v[34:37]
	v_mfma_f32_16x16x32_bf16 v[30:33], v[180:183], v[172:175], v[30:33]
	v_mfma_f32_16x16x32_bf16 v[26:29], v[184:187], v[172:175], v[26:29]
	v_mfma_f32_16x16x32_bf16 v[22:25], v[188:191], v[172:175], v[22:25]
	v_mfma_f32_16x16x32_bf16 v[18:21], v[192:195], v[172:175], v[18:21]
	v_mfma_f32_16x16x32_bf16 v[14:17], v[180:183], v[176:179], v[14:17]
	v_mfma_f32_16x16x32_bf16 v[10:13], v[184:187], v[176:179], v[10:13]
	v_mfma_f32_16x16x32_bf16 v[6:9], v[188:191], v[176:179], v[6:9]
	v_mfma_f32_16x16x32_bf16 v[2:5], v[192:195], v[176:179], v[2:5]
	s_setprio 0
	s_waitcnt vmcnt(0)
	s_waitcnt lgkmcnt(0)
	s_barrier
	ds_read_b128 v[138:141], v153 offset:24576
	ds_read_b128 v[142:145], v153 offset:25600
	ds_read_b128 v[156:159], v153 offset:26624
	ds_read_b128 v[160:163], v153 offset:27648
	ds_read_b128 v[164:167], v153 offset:28672
	ds_read_b128 v[168:171], v153 offset:29696
	ds_read_b128 v[172:175], v153 offset:30720
	ds_read_b128 v[176:179], v153 offset:31744
	ds_read_b128 v[180:183], v154 offset:40960
	ds_read_b128 v[184:187], v154 offset:41984
	ds_read_b128 v[188:191], v154 offset:43008
	ds_read_b128 v[192:195], v154 offset:44032
	s_setprio 1
	s_waitcnt lgkmcnt(0)
	v_mfma_f32_16x16x32_bf16 v[126:129], v[180:183], v[138:141], v[126:129]
	v_mfma_f32_16x16x32_bf16 v[122:125], v[184:187], v[138:141], v[122:125]
	v_mfma_f32_16x16x32_bf16 v[118:121], v[188:191], v[138:141], v[118:121]
	v_mfma_f32_16x16x32_bf16 v[114:117], v[192:195], v[138:141], v[114:117]
	v_mfma_f32_16x16x32_bf16 v[110:113], v[180:183], v[142:145], v[110:113]
	v_mfma_f32_16x16x32_bf16 v[106:109], v[184:187], v[142:145], v[106:109]
	v_mfma_f32_16x16x32_bf16 v[102:105], v[188:191], v[142:145], v[102:105]
	v_mfma_f32_16x16x32_bf16 v[98:101], v[192:195], v[142:145], v[98:101]
	v_mfma_f32_16x16x32_bf16 v[94:97], v[180:183], v[156:159], v[94:97]
	v_mfma_f32_16x16x32_bf16 v[90:93], v[184:187], v[156:159], v[90:93]
	v_mfma_f32_16x16x32_bf16 v[86:89], v[188:191], v[156:159], v[86:89]
	v_mfma_f32_16x16x32_bf16 v[82:85], v[192:195], v[156:159], v[82:85]
	v_mfma_f32_16x16x32_bf16 v[78:81], v[180:183], v[160:163], v[78:81]
	v_mfma_f32_16x16x32_bf16 v[74:77], v[184:187], v[160:163], v[74:77]
	v_mfma_f32_16x16x32_bf16 v[70:73], v[188:191], v[160:163], v[70:73]
	v_mfma_f32_16x16x32_bf16 v[66:69], v[192:195], v[160:163], v[66:69]
	v_mfma_f32_16x16x32_bf16 v[62:65], v[180:183], v[164:167], v[62:65]
	v_mfma_f32_16x16x32_bf16 v[58:61], v[184:187], v[164:167], v[58:61]
	v_mfma_f32_16x16x32_bf16 v[54:57], v[188:191], v[164:167], v[54:57]
	v_mfma_f32_16x16x32_bf16 v[50:53], v[192:195], v[164:167], v[50:53]
	v_mfma_f32_16x16x32_bf16 v[46:49], v[180:183], v[168:171], v[46:49]
	v_mfma_f32_16x16x32_bf16 v[42:45], v[184:187], v[168:171], v[42:45]
	v_mfma_f32_16x16x32_bf16 v[38:41], v[188:191], v[168:171], v[38:41]
	v_mfma_f32_16x16x32_bf16 v[34:37], v[192:195], v[168:171], v[34:37]
	v_mfma_f32_16x16x32_bf16 v[30:33], v[180:183], v[172:175], v[30:33]
	v_mfma_f32_16x16x32_bf16 v[26:29], v[184:187], v[172:175], v[26:29]
	v_mfma_f32_16x16x32_bf16 v[22:25], v[188:191], v[172:175], v[22:25]
	v_mfma_f32_16x16x32_bf16 v[18:21], v[192:195], v[172:175], v[18:21]
	v_mfma_f32_16x16x32_bf16 v[14:17], v[180:183], v[176:179], v[14:17]
	v_mfma_f32_16x16x32_bf16 v[10:13], v[184:187], v[176:179], v[10:13]
	v_mfma_f32_16x16x32_bf16 v[6:9], v[188:191], v[176:179], v[6:9]
	v_mfma_f32_16x16x32_bf16 v[2:5], v[192:195], v[176:179], v[2:5]
	s_setprio 0
	v_add_u32_e32 v155, s44, v151
	s_mov_b32 s2, 0x38e38e39
	v_mul_hi_i32 v138, v155, s2
	v_lshrrev_b32_e32 v139, 31, v138
	v_ashrrev_i32_e32 v138, 9, v138
	s_waitcnt lgkmcnt(0)
	v_add_u32_e32 v138, v138, v139
	v_mad_i32_i24 v139, v138, s53, v155
	v_cmp_lt_i32_e32 vcc, s39, v139
	s_barrier
	s_and_saveexec_b64 s[2:3], vcc
	s_xor_b64 s[6:7], exec, s[2:3]
	s_cbranch_execz .LBB0_993
	v_readlane_b32 s2, v252, 34
	s_nop 1
	v_add_u32_e32 v140, s2, v138
	v_lshlrev_b32_e32 v138, 11, v138
	v_readlane_b32 s2, v252, 54
	v_mul_hi_i32_i24_e32 v145, 0x6000, v140
	v_mul_i32_i24_e32 v144, 0x6000, v140
	v_add3_u32 v142, v138, s2, v139

.LBB0_1243:
	s_mul_i32 s8, s3, 0x6000
	s_add_i32 s8, s8, 0
	s_waitcnt vmcnt(6)
	v_add3_u32 v146, s8, v149, v150
	s_waitcnt lgkmcnt(0)
	s_barrier
	v_add3_u32 v248, s8, v148, v150
	ds_read_b128 v[182:185], v248 offset:16384
	ds_read_b128 v[186:189], v248 offset:17408
	ds_read_b128 v[190:193], v248 offset:18432
	ds_read_b128 v[194:197], v248 offset:19456
	ds_read_b128 v[142:145], v146
	ds_read_b128 v[154:157], v146 offset:1024
	ds_read_b128 v[158:161], v146 offset:2048
	ds_read_b128 v[162:165], v146 offset:3072
	ds_read_b128 v[166:169], v146 offset:4096
	ds_read_b128 v[170:173], v146 offset:5120
	ds_read_b128 v[174:177], v146 offset:6144
	ds_read_b128 v[178:181], v146 offset:7168
	s_cmp_gt_i32 s3, 0
	s_cselect_b32 s8, -1, 2
	s_add_i32 s8, s8, s3
	s_mulk_i32 s8, 0x6000
	v_lshl_add_u64 v[146:147], v[140:141], 0, s[6:7]
	s_mov_b64 s[10:11], 0x7860080
	s_add_i32 s8, s2, s8
	v_lshl_add_u64 v[198:199], v[146:147], 0, s[10:11]
	s_mov_b32 m0, s8
	s_mov_b64 s[10:11], 0x78e0080
	global_load_lds_dwordx4 v[198:199], off
	v_lshl_add_u64 v[198:199], v[146:147], 0, s[10:11]
	s_add_i32 m0, s8, 0x1000
	s_mov_b64 s[10:11], 0x7960080
	global_load_lds_dwordx4 v[198:199], off
	v_lshl_add_u64 v[198:199], v[146:147], 0, s[10:11]
	s_add_i32 m0, s8, 0x2000
	s_mov_b64 s[10:11], 0x79e0080
	global_load_lds_dwordx4 v[198:199], off
	v_lshl_add_u64 v[146:147], v[146:147], 0, s[10:11]
	s_add_i32 m0, s8, 0x3000
	s_mov_b64 s[10:11], 0x2330080
	global_load_lds_dwordx4 v[146:147], off
	v_lshl_add_u64 v[146:147], v[138:139], 0, s[6:7]
	v_lshl_add_u64 v[198:199], v[146:147], 0, s[10:11]
	s_add_i32 m0, s8, 0x4000
	s_mov_b64 s[10:11], 0x23b0080
	global_load_lds_dwordx4 v[198:199], off
	v_lshl_add_u64 v[146:147], v[146:147], 0, s[10:11]
	s_add_i32 m0, s8, 0x5000
	s_nop 0
	global_load_lds_dwordx4 v[146:147], off
	s_setprio 1
	s_waitcnt lgkmcnt(7)
	v_mfma_f32_16x16x32_bf16 v[126:129], v[182:185], v[142:145], v[126:129]
	v_mfma_f32_16x16x32_bf16 v[122:125], v[186:189], v[142:145], v[122:125]
	v_mfma_f32_16x16x32_bf16 v[118:121], v[190:193], v[142:145], v[118:121]
	v_mfma_f32_16x16x32_bf16 v[114:117], v[194:197], v[142:145], v[114:117]
	s_waitcnt lgkmcnt(6)
	v_mfma_f32_16x16x32_bf16 v[110:113], v[182:185], v[154:157], v[110:113]
	v_mfma_f32_16x16x32_bf16 v[106:109], v[186:189], v[154:157], v[106:109]
	v_mfma_f32_16x16x32_bf16 v[102:105], v[190:193], v[154:157], v[102:105]
	v_mfma_f32_16x16x32_bf16 v[98:101], v[194:197], v[154:157], v[98:101]
	s_waitcnt lgkmcnt(5)
	v_mfma_f32_16x16x32_bf16 v[94:97], v[182:185], v[158:161], v[94:97]
	v_mfma_f32_16x16x32_bf16 v[90:93], v[186:189], v[158:161], v[90:93]
	v_mfma_f32_16x16x32_bf16 v[86:89], v[190:193], v[158:161], v[86:89]
	v_mfma_f32_16x16x32_bf16 v[82:85], v[194:197], v[158:161], v[82:85]
	s_waitcnt lgkmcnt(4)
	v_mfma_f32_16x16x32_bf16 v[78:81], v[182:185], v[162:165], v[78:81]
	v_mfma_f32_16x16x32_bf16 v[74:77], v[186:189], v[162:165], v[74:77]
	v_mfma_f32_16x16x32_bf16 v[70:73], v[190:193], v[162:165], v[70:73]
	v_mfma_f32_16x16x32_bf16 v[66:69], v[194:197], v[162:165], v[66:69]
	s_waitcnt lgkmcnt(3)
	v_mfma_f32_16x16x32_bf16 v[62:65], v[182:185], v[166:169], v[62:65]
	v_mfma_f32_16x16x32_bf16 v[58:61], v[186:189], v[166:169], v[58:61]
	v_mfma_f32_16x16x32_bf16 v[54:57], v[190:193], v[166:169], v[54:57]
	v_mfma_f32_16x16x32_bf16 v[50:53], v[194:197], v[166:169], v[50:53]
	s_waitcnt lgkmcnt(2)
	v_mfma_f32_16x16x32_bf16 v[46:49], v[182:185], v[170:173], v[46:49]
	v_mfma_f32_16x16x32_bf16 v[42:45], v[186:189], v[170:173], v[42:45]
	v_mfma_f32_16x16x32_bf16 v[38:41], v[190:193], v[170:173], v[38:41]
	v_mfma_f32_16x16x32_bf16 v[34:37], v[194:197], v[170:173], v[34:37]
	s_waitcnt lgkmcnt(1)
	v_mfma_f32_16x16x32_bf16 v[30:33], v[182:185], v[174:177], v[30:33]
	v_mfma_f32_16x16x32_bf16 v[26:29], v[186:189], v[174:177], v[26:29]
	v_mfma_f32_16x16x32_bf16 v[22:25], v[190:193], v[174:177], v[22:25]
	v_mfma_f32_16x16x32_bf16 v[18:21], v[194:197], v[174:177], v[18:21]
	s_waitcnt lgkmcnt(0)
	v_mfma_f32_16x16x32_bf16 v[14:17], v[182:185], v[178:181], v[14:17]
	v_mfma_f32_16x16x32_bf16 v[10:13], v[186:189], v[178:181], v[10:13]
	v_mfma_f32_16x16x32_bf16 v[6:9], v[190:193], v[178:181], v[6:9]
	v_mfma_f32_16x16x32_bf16 v[2:5], v[194:197], v[178:181], v[2:5]
	s_setprio 0
	s_add_i32 s3, s3, 1
	s_cmp_lg_u32 s3, 3
	s_cselect_b32 s3, s3, 0
	s_add_u32 s6, s6, 64
	s_addc_u32 s7, s7, 0
	s_cmpk_eq_i32 s6, 0x1f80
	s_cbranch_scc0 .LBB0_1243
	s_mul_i32 s2, s3, 0x6000
	s_add_i32 s6, s2, 0
	s_waitcnt vmcnt(6)
	v_add3_u32 v146, s6, v149, v150
	s_waitcnt lgkmcnt(0)
	s_barrier
	ds_read_b128 v[138:141], v146
	ds_read_b128 v[142:145], v146 offset:1024
	ds_read_b128 v[154:157], v146 offset:2048
	ds_read_b128 v[158:161], v146 offset:3072
	ds_read_b128 v[162:165], v146 offset:4096
	ds_read_b128 v[166:169], v146 offset:5120
	ds_read_b128 v[170:173], v146 offset:6144
	ds_read_b128 v[174:177], v146 offset:7168
	v_add3_u32 v146, s6, v148, v150
	ds_read_b128 v[178:181], v146 offset:16384
	ds_read_b128 v[182:185], v146 offset:17408
	ds_read_b128 v[186:189], v146 offset:18432
	ds_read_b128 v[190:193], v146 offset:19456
	s_setprio 1
	s_waitcnt lgkmcnt(0)
	v_mfma_f32_16x16x32_bf16 v[126:129], v[178:181], v[138:141], v[126:129]
	v_mfma_f32_16x16x32_bf16 v[122:125], v[182:185], v[138:141], v[122:125]
	v_mfma_f32_16x16x32_bf16 v[118:121], v[186:189], v[138:141], v[118:121]
	v_mfma_f32_16x16x32_bf16 v[114:117], v[190:193], v[138:141], v[114:117]
	v_mfma_f32_16x16x32_bf16 v[110:113], v[178:181], v[142:145], v[110:113]
	v_mfma_f32_16x16x32_bf16 v[106:109], v[182:185], v[142:145], v[106:109]
	v_mfma_f32_16x16x32_bf16 v[102:105], v[186:189], v[142:145], v[102:105]
	v_mfma_f32_16x16x32_bf16 v[98:101], v[190:193], v[142:145], v[98:101]
	v_mfma_f32_16x16x32_bf16 v[94:97], v[178:181], v[154:157], v[94:97]
	v_mfma_f32_16x16x32_bf16 v[90:93], v[182:185], v[154:157], v[90:93]
	v_mfma_f32_16x16x32_bf16 v[86:89], v[186:189], v[154:157], v[86:89]
	v_mfma_f32_16x16x32_bf16 v[82:85], v[190:193], v[154:157], v[82:85]
	v_mfma_f32_16x16x32_bf16 v[78:81], v[178:181], v[158:161], v[78:81]
	v_mfma_f32_16x16x32_bf16 v[74:77], v[182:185], v[158:161], v[74:77]
	v_mfma_f32_16x16x32_bf16 v[70:73], v[186:189], v[158:161], v[70:73]
	v_mfma_f32_16x16x32_bf16 v[66:69], v[190:193], v[158:161], v[66:69]
	v_mfma_f32_16x16x32_bf16 v[62:65], v[178:181], v[162:165], v[62:65]
	v_mfma_f32_16x16x32_bf16 v[58:61], v[182:185], v[162:165], v[58:61]
	v_mfma_f32_16x16x32_bf16 v[54:57], v[186:189], v[162:165], v[54:57]
	v_mfma_f32_16x16x32_bf16 v[50:53], v[190:193], v[162:165], v[50:53]
	v_mfma_f32_16x16x32_bf16 v[46:49], v[178:181], v[166:169], v[46:49]
	v_mfma_f32_16x16x32_bf16 v[42:45], v[182:185], v[166:169], v[42:45]
	v_mfma_f32_16x16x32_bf16 v[38:41], v[186:189], v[166:169], v[38:41]
	v_mfma_f32_16x16x32_bf16 v[34:37], v[190:193], v[166:169], v[34:37]
	v_mfma_f32_16x16x32_bf16 v[30:33], v[178:181], v[170:173], v[30:33]
	v_mfma_f32_16x16x32_bf16 v[26:29], v[182:185], v[170:173], v[26:29]
	v_mfma_f32_16x16x32_bf16 v[22:25], v[186:189], v[170:173], v[22:25]
	v_mfma_f32_16x16x32_bf16 v[18:21], v[190:193], v[170:173], v[18:21]
	v_mfma_f32_16x16x32_bf16 v[14:17], v[178:181], v[174:177], v[14:17]
	v_mfma_f32_16x16x32_bf16 v[10:13], v[182:185], v[174:177], v[10:13]
	v_mfma_f32_16x16x32_bf16 v[6:9], v[186:189], v[174:177], v[6:9]
	v_mfma_f32_16x16x32_bf16 v[2:5], v[190:193], v[174:177], v[2:5]
	s_setprio 0
	s_addk_i32 s2, 0x6000
	s_cmp_lg_u32 s3, 2
	s_cselect_b32 s2, s2, 0
	s_add_i32 s2, s2, 0
	s_waitcnt vmcnt(0)
	v_add3_u32 v146, s2, v149, v150
	s_waitcnt lgkmcnt(0)
	s_barrier
	ds_read_b128 v[138:141], v146
	ds_read_b128 v[142:145], v146 offset:1024
	ds_read_b128 v[154:157], v146 offset:2048
	ds_read_b128 v[158:161], v146 offset:3072
	ds_read_b128 v[162:165], v146 offset:4096
	ds_read_b128 v[166:169], v146 offset:5120
	ds_read_b128 v[170:173], v146 offset:6144
	ds_read_b128 v[174:177], v146 offset:7168
	v_add3_u32 v146, s2, v148, v150
	ds_read_b128 v[178:181], v146 offset:16384
	ds_read_b128 v[182:185], v146 offset:17408
	ds_read_b128 v[186:189], v146 offset:18432
	ds_read_b128 v[190:193], v146 offset:19456
	s_setprio 1
	s_waitcnt lgkmcnt(0)
	v_mfma_f32_16x16x32_bf16 v[126:129], v[178:181], v[138:141], v[126:129]
	v_mfma_f32_16x16x32_bf16 v[122:125], v[182:185], v[138:141], v[122:125]
	v_mfma_f32_16x16x32_bf16 v[118:121], v[186:189], v[138:141], v[118:121]
	v_mfma_f32_16x16x32_bf16 v[114:117], v[190:193], v[138:141], v[114:117]
	v_mfma_f32_16x16x32_bf16 v[110:113], v[178:181], v[142:145], v[110:113]
	v_mfma_f32_16x16x32_bf16 v[106:109], v[182:185], v[142:145], v[106:109]
	v_mfma_f32_16x16x32_bf16 v[102:105], v[186:189], v[142:145], v[102:105]
	v_mfma_f32_16x16x32_bf16 v[98:101], v[190:193], v[142:145], v[98:101]
	v_mfma_f32_16x16x32_bf16 v[94:97], v[178:181], v[154:157], v[94:97]
	v_mfma_f32_16x16x32_bf16 v[90:93], v[182:185], v[154:157], v[90:93]
	v_mfma_f32_16x16x32_bf16 v[86:89], v[186:189], v[154:157], v[86:89]
	v_mfma_f32_16x16x32_bf16 v[82:85], v[190:193], v[154:157], v[82:85]
	v_mfma_f32_16x16x32_bf16 v[78:81], v[178:181], v[158:161], v[78:81]
	v_mfma_f32_16x16x32_bf16 v[74:77], v[182:185], v[158:161], v[74:77]
	v_mfma_f32_16x16x32_bf16 v[70:73], v[186:189], v[158:161], v[70:73]
	v_mfma_f32_16x16x32_bf16 v[66:69], v[190:193], v[158:161], v[66:69]
	v_mfma_f32_16x16x32_bf16 v[62:65], v[178:181], v[162:165], v[62:65]
	v_mfma_f32_16x16x32_bf16 v[58:61], v[182:185], v[162:165], v[58:61]
	v_mfma_f32_16x16x32_bf16 v[54:57], v[186:189], v[162:165], v[54:57]
	v_mfma_f32_16x16x32_bf16 v[50:53], v[190:193], v[162:165], v[50:53]
	v_mfma_f32_16x16x32_bf16 v[46:49], v[178:181], v[166:169], v[46:49]
	v_mfma_f32_16x16x32_bf16 v[42:45], v[182:185], v[166:169], v[42:45]
	v_mfma_f32_16x16x32_bf16 v[38:41], v[186:189], v[166:169], v[38:41]
	v_mfma_f32_16x16x32_bf16 v[34:37], v[190:193], v[166:169], v[34:37]
	v_mfma_f32_16x16x32_bf16 v[30:33], v[178:181], v[170:173], v[30:33]
	v_mfma_f32_16x16x32_bf16 v[26:29], v[182:185], v[170:173], v[26:29]
	v_mfma_f32_16x16x32_bf16 v[22:25], v[186:189], v[170:173], v[22:25]
	v_mfma_f32_16x16x32_bf16 v[18:21], v[190:193], v[170:173], v[18:21]
	v_mfma_f32_16x16x32_bf16 v[14:17], v[178:181], v[174:177], v[14:17]
	v_mfma_f32_16x16x32_bf16 v[10:13], v[182:185], v[174:177], v[10:13]
	v_mfma_f32_16x16x32_bf16 v[6:9], v[186:189], v[174:177], v[6:9]
	v_mfma_f32_16x16x32_bf16 v[2:5], v[190:193], v[174:177], v[2:5]
	s_setprio 0
	v_add_u32_e32 v153, s40, v151
	s_mov_b32 s2, 0x38e38e39
	v_mul_hi_i32 v138, v153, s2
	v_lshrrev_b32_e32 v139, 31, v138
	v_ashrrev_i32_e32 v138, 9, v138
	s_waitcnt lgkmcnt(0)
	v_add_u32_e32 v138, v138, v139
	v_mad_i32_i24 v139, v138, s53, v153
	v_cmp_lt_i32_e32 vcc, s12, v139
	s_barrier
	s_and_saveexec_b64 s[2:3], vcc
	s_xor_b64 s[6:7], exec, s[2:3]
	s_cbranch_execz .LBB0_1246
	v_readlane_b32 s2, v252, 34
	s_nop 1
	v_add_u32_e32 v140, s2, v138
	v_lshlrev_b32_e32 v138, 11, v138
	v_readlane_b32 s2, v252, 54
	v_mul_hi_i32_i24_e32 v145, 0x6000, v140
	v_mul_i32_i24_e32 v144, 0x6000, v140
	v_add3_u32 v142, v138, s2, v139
